# v33 plus q/k head-norm loop processes two adjacent heads of a row per iteration (all loads before one wait, half the round trips)
# speedup vs baseline: 1.0106x; 1.0106x over previous
; __device__ __forceinline__ unsigned cvtpk(float lo, float hi) { unsigned r; asm volatile("v_cvt_pk_bf16_f32 %0, %1, %2" : "=v"(r) : "v"(lo), "v"(hi)); return r; }
; __device__ __forceinline__ float bflo(unsigned w) { return __uint_as_float(w << 16); }
; __device__ __forceinline__ float bfhi(unsigned w) { return __uint_as_float(w & 0xffff0000u); }
; __device__ __forceinline__ void ew_phase(const Params& p, int l) {
;     ...
;         for (long it = grp; it < (long)ROWS * 20; it += ngrp) { const int row = (int)(it / 20), head = (int)(it % 20);
;             const bf16_t* src_ = P + (size_t)row * INC + (head < 16 ? OQ + head * 128 : OKK + (head - 16) * 128) + base;
;             bf16_t* dst_ = (head < 16) ? (P + (size_t)row * INC + OQ + head * 128 + base) : (KC + ((size_t)(head - 16) * ROWS + row) * 128 + base);
;             const float* gn = (head < 16 ? p.in[I_QN] : p.in[I_KN]) + (size_t)l * 128 + base;
;             const u32x2 wa = *(const u32x2*)src_, wb = *(const u32x2*)(src_ + 32);
;             const f32x4 ga = *(const f32x4*)gn, gb = *(const f32x4*)(gn + 32);
;             float a[4] = {bflo(wa.x), bfhi(wa.x), bflo(wa.y), bfhi(wa.y)}, b[4] = {bflo(wb.x), bfhi(wb.x), bflo(wb.y), bfhi(wb.y)};
;             float ss = 0.f;
; #pragma unroll
;             for (int q = 0; q < 4; ++q) ss += a[q] * a[q] + b[q] * b[q];
; #pragma unroll
;             for (int o = 8; o >= 1; o >>= 1) ss += __shfl_xor(ss, o);
;             const float rstd = rsqrtf(ss * (1.0f / 128.0f) + EPS);
; #pragma unroll
;             for (int q = 0; q < 4; ++q) { a[q] = a[q] * rstd * ga[q]; b[q] = b[q] * rstd * gb[q]; }
;             if (row >= CTX) { const int tk = row - CTX, pos = (t & 8) ? (tk & 63) : (tk >> 6);
;                 const f32x4 r01 = *(const f32x4*)(rope + pos * 32 + fi), r23 = *(const f32x4*)(rope + pos * 32 + fi + 2);
;                 const float cs[4] = {r01[0], r01[2], r23[0], r23[2]}, sn[4] = {r01[1], r01[3], r23[1], r23[3]};
; #pragma unroll
;                 for (int q = 0; q < 4; ++q) { const float x0 = a[q], x1 = b[q]; a[q] = x0 * cs[q] - x1 * sn[q]; b[q] = x0 * sn[q] + x1 * cs[q]; } }
;             u32x2 oa, ob; oa.x = cvtpk(a[0], a[1]); oa.y = cvtpk(a[2], a[3]); ob.x = cvtpk(b[0], b[1]); ob.y = cvtpk(b[2], b[3]);
;             *(u32x2*)dst_ = oa; *(u32x2*)(dst_ + 32) = ob;
.LBB0_244:
	s_andn2_b64 vcc, exec, s[0:1]
	s_cbranch_vccnz .LBB0_282
	s_cmp_gt_i32 s46, 5
	s_mov_b64 s[0:1], -1
	s_cbranch_scc0 .LBB0_266
	v_mov_b32_e32 v0, v190
	v_readlane_b32 s0, v246, 21
	v_readlane_b32 s1, v246, 22
	v_ashrrev_i32_e32 v1, 31, v0
	s_mov_b32 s21, s86
	v_lshl_add_u64 v[114:115], s[0:1], 0, v[0:1]
	v_ashrrev_i64 v[2:3], 4, v[114:115]
	s_mov_b64 s[0:1], 0x29400
	s_mov_b32 s20, s85
	v_cmp_gt_i64_e32 vcc, s[0:1], v[2:3]
	s_and_saveexec_b64 s[4:5], vcc
	s_cbranch_execz .LBB0_253
	v_lshlrev_b32_e32 v5, 2, v0
	v_and_b32_e32 v5, 28, v5
	v_and_b32_e32 v4, 8, v0
	v_and_b32_e32 v6, 64, v191
	v_lshlrev_b32_e32 v96, 3, v5
	v_cmp_eq_u32_e32 vcc, 0, v4
	v_lshl_or_b32 v4, v4, 3, v5
	v_add_u32_e32 v8, 64, v6
	v_lshl_add_u64 v[6:7], s[54:55], 0, v[96:97]
	s_mov_b64 s[0:1], 0x1c8f0000
	v_xor_b32_e32 v5, 8, v191
	v_lshl_add_u64 v[6:7], v[6:7], 0, s[0:1]
	v_cmp_lt_i32_e64 s[0:1], v5, v8
	v_xor_b32_e32 v9, 4, v191
	v_xor_b32_e32 v10, 2, v191
	v_cndmask_b32_e64 v5, v191, v5, s[0:1]
	v_cmp_lt_i32_e64 s[0:1], v9, v8
	v_lshlrev_b32_e32 v5, 2, v5
	s_mov_b64 s[14:15], 0
	v_cndmask_b32_e64 v9, v191, v9, s[0:1]
	v_cmp_lt_i32_e64 s[0:1], v10, v8
	v_lshlrev_b32_e32 v9, 2, v9
	s_nop 0
	v_cndmask_b32_e64 v10, v191, v10, s[0:1]
	v_lshlrev_b32_e32 v26, 2, v10
	v_xor_b32_e32 v10, 1, v191
	v_cmp_lt_i32_e64 s[0:1], v10, v8
	s_nop 1
	v_cndmask_b32_e64 v8, v191, v10, s[0:1]
	v_readlane_b32 s0, v246, 23
	v_lshlrev_b32_e32 v27, 2, v8
	v_lshlrev_b64 v[2:3], 1, v[2:3]
	v_lshlrev_b32_e32 v8, 7, v2
	s_lshl_b32 s18, s0, 8
	v_readlane_b32 s1, v246, 24
	s_branch .LBB0_249
.LBB0_248:
	s_or_b64 exec, exec, s[16:17]
	v_lshl_add_u64 v[10:11], v[10:11], 0, v[96:97]
	v_cvt_pk_bf16_f32 v12, v20, v23
	v_cvt_pk_bf16_f32 v13, v14, v17
	v_cvt_pk_bf16_f32 v14, v18, v19
	v_cvt_pk_bf16_f32 v15, v24, v25
	v_mov_b32_e32 v96, v119
	s_mov_b32 s0, 0x800000
	v_lshl_add_u64 v[210:211], v[10:11], 0, v[96:97]
	v_lshlrev_b32_e32 v220, 16, v218
	v_and_b32_e32 v221, 0xffff0000, v214
	v_lshlrev_b32_e32 v216, 16, v214
	v_and_b32_e32 v217, 0xffff0000, v218
	v_pk_mul_f32 v[224:225], v[220:221], v[220:221]
	v_lshlrev_b32_e32 v238, 16, v215
	v_and_b32_e32 v239, 0xffff0000, v219
	v_pk_fma_f32 v[224:225], v[216:217], v[216:217], v[224:225]
	v_lshlrev_b32_e32 v214, 16, v219
	v_and_b32_e32 v215, 0xffff0000, v215
	v_pk_mul_f32 v[218:219], v[238:239], v[238:239]
	v_add_f32_e32 v213, v224, v225
	v_pk_fma_f32 v[218:219], v[214:215], v[214:215], v[218:219]
	v_mov_b32_e32 v222, v216
	v_add_f32_e32 v213, v218, v213
	v_add_f32_e32 v213, v219, v213
	ds_bpermute_b32 v218, v5, v213
	v_mov_b32_e32 v223, v221
	v_mov_b32_e32 v236, v232
	v_mov_b32_e32 v237, v229
	v_mov_b32_e32 v229, v233
	s_waitcnt lgkmcnt(0)
	v_add_f32_e32 v213, v213, v218
	ds_bpermute_b32 v218, v9, v213
	v_mov_b32_e32 v240, v238
	v_mov_b32_e32 v241, v215
	s_waitcnt lgkmcnt(0)
	v_add_f32_e32 v213, v213, v218
	ds_bpermute_b32 v218, v26, v213
	s_waitcnt lgkmcnt(0)
	v_add_f32_e32 v213, v213, v218
	ds_bpermute_b32 v218, v27, v213
	s_waitcnt lgkmcnt(0)
	v_add_f32_e32 v213, v213, v218
	v_fmamk_f32 v213, v213, 0x3c000000, v193
	v_cmp_gt_f32_e64 s[0:1], s0, v213
	v_mul_f32_e32 v218, 0x4b800000, v213
	s_nop 0
	v_cndmask_b32_e64 v213, v213, v218, s[0:1]
	v_rsq_f32_e32 v213, v213
	s_nop 0
	v_mul_f32_e32 v218, 0x45800000, v213
	v_cndmask_b32_e64 v224, v213, v218, s[0:1]
	v_pk_mul_f32 v[218:219], v[224:225], v[220:221] op_sel_hi:[0,1]
	v_pk_mul_f32 v[216:217], v[224:225], v[216:217] op_sel_hi:[0,1]
	v_pk_mul_f32 v[242:243], v[224:225], v[222:223] op_sel_hi:[0,1]
	v_pk_mul_f32 v[222:223], v[236:237], v[216:217]
	v_pk_mul_f32 v[220:221], v[228:229], v[218:219]
	v_pk_mul_f32 v[214:215], v[224:225], v[214:215] op_sel_hi:[0,1]
	v_pk_mul_f32 v[216:217], v[224:225], v[238:239] op_sel_hi:[0,1]
	v_pk_mul_f32 v[224:225], v[224:225], v[240:241] op_sel_hi:[0,1]
	v_mov_b32_e32 v228, v234
	v_mov_b32_e32 v229, v231
	v_mov_b32_e32 v231, v235
	s_mov_b64 s[0:1], 0x13ff
	v_pk_mul_f32 v[218:219], v[232:233], v[242:243]
	v_pk_mul_f32 v[216:217], v[228:229], v[216:217]
	v_pk_mul_f32 v[214:215], v[230:231], v[214:215]
	v_pk_mul_f32 v[224:225], v[234:235], v[224:225]
	v_cmp_lt_i64_e64 s[0:1], s[0:1], v[2:3]
	s_and_saveexec_b64 s[16:17], s[0:1]
	s_cbranch_execz .Lqk_bjoin
	v_mov_b32_e32 v236, v222
	v_mov_b32_e32 v237, v221
	v_mov_b32_e32 v218, v220
	v_mov_b32_e32 v219, v223
	v_mov_b32_e32 v224, v214
	v_mov_b32_e32 v225, v217
	v_mov_b32_e32 v238, v121
	v_mov_b32_e32 v239, v123
	v_mov_b32_e32 v212, v120
	v_mov_b32_e32 v213, v122
	v_pk_mul_f32 v[236:237], v[236:237], v[238:239]
	s_nop 0
	v_pk_fma_f32 v[212:213], v[218:219], v[212:213], v[236:237] neg_lo:[0,0,1] neg_hi:[0,0,1]
	v_mov_b32_e32 v218, v120
	v_mov_b32_e32 v219, v123
	v_pk_mul_f32 v[218:219], v[222:223], v[218:219]
	v_mov_b32_e32 v222, v121
	v_mov_b32_e32 v223, v122
	v_pk_fma_f32 v[218:219], v[220:221], v[222:223], v[218:219]
	v_mov_b32_e32 v222, v216
	v_mov_b32_e32 v223, v215
	v_mov_b32_e32 v120, v125
	v_mov_b32_e32 v121, v127
	v_mov_b32_e32 v220, v124
	v_mov_b32_e32 v221, v126
	v_pk_mul_f32 v[222:223], v[222:223], v[120:121]
	s_nop 0
	v_pk_fma_f32 v[120:121], v[224:225], v[220:221], v[222:223] neg_lo:[0,0,1] neg_hi:[0,0,1]
	v_mov_b32_e32 v221, v127
	v_pk_mul_f32 v[216:217], v[216:217], v[220:221]
	v_mov_b32_e32 v220, v125
	v_mov_b32_e32 v221, v126
	v_pk_fma_f32 v[224:225], v[214:215], v[220:221], v[216:217]
	v_mov_b32_e32 v220, v212
	v_mov_b32_e32 v223, v213
	v_mov_b32_e32 v214, v120
	v_mov_b32_e32 v217, v121
; __device__ __forceinline__ unsigned cvtpk(float lo, float hi) { unsigned r; asm volatile("v_cvt_pk_bf16_f32 %0, %1, %2" : "=v"(r) : "v"(lo), "v"(hi)); return r; }
; __device__ __forceinline__ float bflo(unsigned w) { return __uint_as_float(w << 16); }
; __device__ __forceinline__ float bfhi(unsigned w) { return __uint_as_float(w & 0xffff0000u); }
; __device__ __forceinline__ void ew_phase(const Params& p, int l) {
;     ...
;         for (long it = grp; it < (long)ROWS * 20; it += ngrp) { const int row = (int)(it / 20), head = (int)(it % 20);
;             const bf16_t* src_ = P + (size_t)row * INC + (head < 16 ? OQ + head * 128 : OKK + (head - 16) * 128) + base;
;             bf16_t* dst_ = (head < 16) ? (P + (size_t)row * INC + OQ + head * 128 + base) : (KC + ((size_t)(head - 16) * ROWS + row) * 128 + base);
;             const float* gn = (head < 16 ? p.in[I_QN] : p.in[I_KN]) + (size_t)l * 128 + base;
;             const u32x2 wa = *(const u32x2*)src_, wb = *(const u32x2*)(src_ + 32);
;             const f32x4 ga = *(const f32x4*)gn, gb = *(const f32x4*)(gn + 32);
;             float a[4] = {bflo(wa.x), bfhi(wa.x), bflo(wa.y), bfhi(wa.y)}, b[4] = {bflo(wb.x), bfhi(wb.x), bflo(wb.y), bfhi(wb.y)};
;             float ss = 0.f;
; #pragma unroll
;             for (int q = 0; q < 4; ++q) ss += a[q] * a[q] + b[q] * b[q];
; #pragma unroll
;             for (int o = 8; o >= 1; o >>= 1) ss += __shfl_xor(ss, o);
;             const float rstd = rsqrtf(ss * (1.0f / 128.0f) + EPS);
; #pragma unroll
;             for (int q = 0; q < 4; ++q) { a[q] = a[q] * rstd * ga[q]; b[q] = b[q] * rstd * gb[q]; }
;             if (row >= CTX) { const int tk = row - CTX, pos = (t & 8) ? (tk & 63) : (tk >> 6);
;                 const f32x4 r01 = *(const f32x4*)(rope + pos * 32 + fi), r23 = *(const f32x4*)(rope + pos * 32 + fi + 2);
;                 const float cs[4] = {r01[0], r01[2], r23[0], r23[2]}, sn[4] = {r01[1], r01[3], r23[1], r23[3]};
; #pragma unroll
;                 for (int q = 0; q < 4; ++q) { const float x0 = a[q], x1 = b[q]; a[q] = x0 * cs[q] - x1 * sn[q]; b[q] = x0 * sn[q] + x1 * cs[q]; } }
;             u32x2 oa, ob; oa.x = cvtpk(a[0], a[1]); oa.y = cvtpk(a[2], a[3]); ob.x = cvtpk(b[0], b[1]); ob.y = cvtpk(b[2], b[3]);
;             *(u32x2*)dst_ = oa; *(u32x2*)(dst_ + 32) = ob;
.Lqk_bjoin:
	s_or_b64 exec, exec, s[16:17]
	v_cvt_pk_bf16_f32 v212, v220, v223
	v_cvt_pk_bf16_f32 v213, v214, v217
	v_cvt_pk_bf16_f32 v214, v218, v219
	v_cvt_pk_bf16_f32 v215, v224, v225
	flat_store_dwordx2 v[10:11], v[12:13]
	flat_store_dwordx2 v[10:11], v[14:15] offset:64
	flat_store_dwordx2 v[210:211], v[212:213]
	flat_store_dwordx2 v[210:211], v[214:215] offset:64
	v_readlane_b32 s0, v246, 23
	v_readlane_b32 s1, v246, 24
	s_nop 0
	s_lshl_b64 s[0:1], s[0:1], 1
	v_add_u32_e32 v8, s18, v8
	v_lshl_add_u64 v[2:3], v[2:3], 0, s[0:1]
	s_mov_b64 s[0:1], 0x293ff
	v_cmp_lt_i64_e64 s[0:1], s[0:1], v[2:3]
	s_or_b64 s[14:15], s[0:1], s[14:15]
	s_andn2_b64 exec, exec, s[14:15]
	s_cbranch_execz .LBB0_253
.LBB0_249:
	v_mul_hi_u32 v96, v2, s91
	v_mad_u64_u32 v[10:11], s[0:1], v3, s91, v[96:97]
	v_mov_b32_e32 v96, v11
	v_mov_b32_e32 v11, v97
	s_mov_b32 s3, 0x66666666
	v_mad_u64_u32 v[10:11], s[0:1], v2, s3, v[10:11]
	v_mov_b32_e32 v10, v11
	v_mov_b32_e32 v11, v97
	v_lshl_add_u64 v[10:11], v[96:97], 0, v[10:11]
	v_mad_u64_u32 v[10:11], s[0:1], v3, s3, v[10:11]
	v_ashrrev_i32_e32 v12, 31, v3
	v_mad_u64_u32 v[10:11], s[0:1], v12, s91, v[10:11]
	v_mul_lo_u32 v13, v12, s3
	v_mul_lo_u32 v12, v12, s91
	v_add3_u32 v11, v12, v11, v13
	v_ashrrev_i64 v[12:13], 3, v[10:11]
	v_lshrrev_b32_e32 v96, 31, v11
	v_lshl_add_u64 v[12:13], v[12:13], 0, v[96:97]
	s_movk_i32 s3, 0xffec
	v_mad_u64_u32 v[16:17], s[0:1], v12, s3, v[2:3]
	v_mov_b32_e32 v10, v17
	v_mad_u64_u32 v[10:11], s[0:1], v13, s3, v[10:11]
	v_sub_u32_e32 v17, v10, v12
	v_mov_b64_e32 v[10:11], s[8:9]
	v_mad_u64_u32 v[10:11], s[0:1], v12, s33, v[10:11]
	v_mov_b32_e32 v14, v11
	v_mad_u64_u32 v[14:15], s[0:1], v13, s33, v[14:15]
	s_movk_i32 s3, 0xf600
	v_mov_b32_e32 v11, v14
	v_mad_u64_u32 v[14:15], s[16:17], v12, s3, v[8:9]
	v_ashrrev_i32_e32 v15, 31, v14
	v_readlane_b32 s72, v247, 2
	v_lshl_add_u64 v[14:15], v[14:15], 1, v[10:11]
	v_readlane_b32 s74, v247, 4
	v_readlane_b32 s75, v247, 5
	v_cmp_lt_i64_e64 s[0:1], 15, v[16:17]
	v_mov_b64_e32 v[10:11], v[14:15]
	v_mov_b64_e32 v[18:19], s[74:75]
	v_readlane_b32 s73, v247, 3
	v_readlane_b32 s76, v247, 6
	v_readlane_b32 s77, v247, 7
	v_readlane_b32 s78, v247, 8
	v_readlane_b32 s79, v247, 9
	v_readlane_b32 s80, v247, 10
	v_readlane_b32 s81, v247, 11
	v_readlane_b32 s82, v247, 12
	v_readlane_b32 s83, v247, 13
	v_readlane_b32 s84, v247, 14
	v_readlane_b32 s85, v247, 15
	v_readlane_b32 s86, v247, 16
	v_readlane_b32 s87, v247, 17
	v_mov_b32_e32 v119, 0x100
	s_and_saveexec_b64 s[16:17], s[0:1]
	s_cbranch_execz .LBB0_251
	v_mov_b32_e32 v119, 0x210000
	v_add_u32_e32 v10, -16, v16
	s_movk_i32 s0, 0x2100
	v_mad_u64_u32 v[10:11], s[0:1], v10, s0, v[12:13]
	v_readlane_b32 s72, v247, 2
	v_lshlrev_b64 v[10:11], 8, v[10:11]
	v_readlane_b32 s76, v247, 6
	v_readlane_b32 s77, v247, 7
	v_lshl_add_u64 v[10:11], s[12:13], 0, v[10:11]
	v_readlane_b32 s73, v247, 3
	v_mov_b64_e32 v[18:19], s[76:77]
	v_readlane_b32 s74, v247, 4
	v_readlane_b32 s75, v247, 5
	v_readlane_b32 s78, v247, 8
	v_readlane_b32 s79, v247, 9
	v_readlane_b32 s80, v247, 10
	v_readlane_b32 s81, v247, 11
	v_readlane_b32 s82, v247, 12
	v_readlane_b32 s83, v247, 13
	v_readlane_b32 s84, v247, 14
	v_readlane_b32 s85, v247, 15
	v_readlane_b32 s86, v247, 16
	v_readlane_b32 s87, v247, 17
; __device__ __forceinline__ float bflo(unsigned w) { return __uint_as_float(w << 16); }
; __device__ __forceinline__ float bfhi(unsigned w) { return __uint_as_float(w & 0xffff0000u); }
; __device__ __forceinline__ void ew_phase(const Params& p, int l) {
;     ...
;         for (long it = grp; it < (long)ROWS * 20; it += ngrp) { const int row = (int)(it / 20), head = (int)(it % 20);
;             const bf16_t* src_ = P + (size_t)row * INC + (head < 16 ? OQ + head * 128 : OKK + (head - 16) * 128) + base;
;             bf16_t* dst_ = (head < 16) ? (P + (size_t)row * INC + OQ + head * 128 + base) : (KC + ((size_t)(head - 16) * ROWS + row) * 128 + base);
;             const float* gn = (head < 16 ? p.in[I_QN] : p.in[I_KN]) + (size_t)l * 128 + base;
;             const u32x2 wa = *(const u32x2*)src_, wb = *(const u32x2*)(src_ + 32);
;             const f32x4 ga = *(const f32x4*)gn, gb = *(const f32x4*)(gn + 32);
;             float a[4] = {bflo(wa.x), bfhi(wa.x), bflo(wa.y), bfhi(wa.y)}, b[4] = {bflo(wb.x), bfhi(wb.x), bflo(wb.y), bfhi(wb.y)};
;             float ss = 0.f;
; #pragma unroll
;             for (int q = 0; q < 4; ++q) ss += a[q] * a[q] + b[q] * b[q];
; #pragma unroll
;             for (int o = 8; o >= 1; o >>= 1) ss += __shfl_xor(ss, o);
;             const float rstd = rsqrtf(ss * (1.0f / 128.0f) + EPS);
; #pragma unroll
;             for (int q = 0; q < 4; ++q) { a[q] = a[q] * rstd * ga[q]; b[q] = b[q] * rstd * gb[q]; }
;             if (row >= CTX) { const int tk = row - CTX, pos = (t & 8) ? (tk & 63) : (tk >> 6);
;                 const f32x4 r01 = *(const f32x4*)(rope + pos * 32 + fi), r23 = *(const f32x4*)(rope + pos * 32 + fi + 2);
.LBB0_251:
	s_or_b64 exec, exec, s[16:17]
	v_readlane_b32 s0, v245, 45
	v_lshlrev_b32_e32 v96, 1, v4
	v_readlane_b32 s1, v245, 46
	v_lshl_add_u64 v[14:15], v[14:15], 0, v[96:97]
	s_nop 0
	v_lshl_add_u64 v[16:17], v[18:19], 0, s[0:1]
	v_lshlrev_b32_e32 v18, 2, v4
	v_mov_b32_e32 v19, v97
	v_lshl_add_u64 v[16:17], v[16:17], 0, v[18:19]
	flat_load_dwordx2 v[18:19], v[14:15]
	flat_load_dwordx2 v[218:219], v[14:15] offset:256
	flat_load_dwordx2 v[214:215], v[14:15] offset:320
	flat_load_dwordx2 v[14:15], v[14:15] offset:64
	global_load_dwordx4 v[28:31], v[16:17], off
	global_load_dwordx4 v[32:35], v[16:17], off offset:128
	global_load_dwordx4 v[228:231], v[16:17], off
	global_load_dwordx4 v[232:235], v[16:17], off offset:128
	s_mov_b64 s[98:99], 0x13ff
	v_cmp_lt_i64_e64 s[98:99], s[98:99], v[2:3]
	s_and_saveexec_b64 s[100:101], s[98:99]
	v_add_u32_e32 v209, 0xffffff00, v12
	v_and_b32_e32 v208, 63, v12
	v_lshrrev_b32_e32 v209, 6, v209
	v_cndmask_b32_e32 v208, v208, v209, vcc
	v_lshlrev_b32_e32 v208, 5, v208
	v_mov_b32_e32 v209, v97
	v_lshl_add_u64 v[208:209], v[208:209], 3, v[6:7]
	flat_load_dwordx4 v[200:203], v[208:209]
	flat_load_dwordx4 v[204:207], v[208:209] offset:16
	flat_load_dwordx4 v[120:123], v[208:209]
	flat_load_dwordx4 v[124:127], v[208:209] offset:16
	s_mov_b64 exec, s[100:101]
	s_mov_b32 s0, 0x800000
	s_waitcnt vmcnt(0) lgkmcnt(0)
	v_lshlrev_b32_e32 v20, 16, v18
	v_and_b32_e32 v21, 0xffff0000, v14
	v_lshlrev_b32_e32 v16, 16, v14
	v_and_b32_e32 v17, 0xffff0000, v18
	v_pk_mul_f32 v[24:25], v[20:21], v[20:21]
	v_lshlrev_b32_e32 v38, 16, v15
	v_and_b32_e32 v39, 0xffff0000, v19
	v_pk_fma_f32 v[24:25], v[16:17], v[16:17], v[24:25]
	v_lshlrev_b32_e32 v14, 16, v19
	v_and_b32_e32 v15, 0xffff0000, v15
	v_pk_mul_f32 v[18:19], v[38:39], v[38:39]
	v_add_f32_e32 v13, v24, v25
	v_pk_fma_f32 v[18:19], v[14:15], v[14:15], v[18:19]
	v_mov_b32_e32 v22, v16
	v_add_f32_e32 v13, v18, v13
	v_add_f32_e32 v13, v19, v13
	ds_bpermute_b32 v18, v5, v13
	v_mov_b32_e32 v23, v21
	v_mov_b32_e32 v36, v32
	v_mov_b32_e32 v37, v29
	v_mov_b32_e32 v29, v33
	s_waitcnt lgkmcnt(0)
	v_add_f32_e32 v13, v13, v18
	ds_bpermute_b32 v18, v9, v13
	v_mov_b32_e32 v40, v38
	v_mov_b32_e32 v41, v15
	s_waitcnt lgkmcnt(0)
	v_add_f32_e32 v13, v13, v18
	ds_bpermute_b32 v18, v26, v13
	s_waitcnt lgkmcnt(0)
	v_add_f32_e32 v13, v13, v18
	ds_bpermute_b32 v18, v27, v13
	s_waitcnt lgkmcnt(0)
	v_add_f32_e32 v13, v13, v18
	v_fmamk_f32 v13, v13, 0x3c000000, v193
	v_cmp_gt_f32_e64 s[0:1], s0, v13
	v_mul_f32_e32 v18, 0x4b800000, v13
	s_nop 0
	v_cndmask_b32_e64 v13, v13, v18, s[0:1]
	v_rsq_f32_e32 v13, v13
	s_nop 0
	v_mul_f32_e32 v18, 0x45800000, v13
	v_cndmask_b32_e64 v24, v13, v18, s[0:1]
	v_pk_mul_f32 v[18:19], v[24:25], v[20:21] op_sel_hi:[0,1]
	v_pk_mul_f32 v[16:17], v[24:25], v[16:17] op_sel_hi:[0,1]
	v_pk_mul_f32 v[42:43], v[24:25], v[22:23] op_sel_hi:[0,1]
	v_pk_mul_f32 v[22:23], v[36:37], v[16:17]
	v_pk_mul_f32 v[20:21], v[28:29], v[18:19]
	v_pk_mul_f32 v[14:15], v[24:25], v[14:15] op_sel_hi:[0,1]
	v_pk_mul_f32 v[16:17], v[24:25], v[38:39] op_sel_hi:[0,1]
	v_pk_mul_f32 v[24:25], v[24:25], v[40:41] op_sel_hi:[0,1]
	v_mov_b32_e32 v28, v34
	v_mov_b32_e32 v29, v31
	v_mov_b32_e32 v31, v35
	s_mov_b64 s[0:1], 0x13ff
	v_pk_mul_f32 v[18:19], v[32:33], v[42:43]
	v_pk_mul_f32 v[16:17], v[28:29], v[16:17]
	v_pk_mul_f32 v[14:15], v[30:31], v[14:15]
	v_pk_mul_f32 v[24:25], v[34:35], v[24:25]
	v_cmp_lt_i64_e64 s[0:1], s[0:1], v[2:3]
	s_and_saveexec_b64 s[16:17], s[0:1]
	s_cbranch_execz .LBB0_248
	v_mov_b32_e32 v36, v22
	v_mov_b32_e32 v37, v21
	v_mov_b32_e32 v18, v20
	v_mov_b32_e32 v19, v23
	v_mov_b32_e32 v24, v14
	v_mov_b32_e32 v25, v17
	s_waitcnt vmcnt(0) lgkmcnt(0)
	v_mov_b32_e32 v38, v201
	v_mov_b32_e32 v39, v203
	v_mov_b32_e32 v12, v200
	v_mov_b32_e32 v13, v202
	v_pk_mul_f32 v[36:37], v[36:37], v[38:39]
	s_nop 0
	v_pk_fma_f32 v[12:13], v[18:19], v[12:13], v[36:37] neg_lo:[0,0,1] neg_hi:[0,0,1]
	v_mov_b32_e32 v18, v200
	v_mov_b32_e32 v19, v203
	v_pk_mul_f32 v[18:19], v[22:23], v[18:19]
	v_mov_b32_e32 v22, v201
	v_mov_b32_e32 v23, v202
	v_pk_fma_f32 v[18:19], v[20:21], v[22:23], v[18:19]
	v_mov_b32_e32 v22, v16
	v_mov_b32_e32 v23, v15
	v_mov_b32_e32 v200, v205
	v_mov_b32_e32 v201, v207
	v_mov_b32_e32 v20, v204
	v_mov_b32_e32 v21, v206
	v_pk_mul_f32 v[22:23], v[22:23], v[200:201]
	s_nop 0
	v_pk_fma_f32 v[200:201], v[24:25], v[20:21], v[22:23] neg_lo:[0,0,1] neg_hi:[0,0,1]
	v_mov_b32_e32 v21, v207
	v_pk_mul_f32 v[16:17], v[16:17], v[20:21]
	v_mov_b32_e32 v20, v205
	v_mov_b32_e32 v21, v206
	v_pk_fma_f32 v[24:25], v[14:15], v[20:21], v[16:17]
	v_mov_b32_e32 v20, v12
	v_mov_b32_e32 v23, v13
	v_mov_b32_e32 v14, v200
	v_mov_b32_e32 v17, v201
	s_branch .LBB0_248
